# far-segment items: closing workgroup barrier after the flag publish removed (other waves start the next item while wave 0 flushes)
# baseline (speedup 1.0000x reference)
.LBB0_565:
	s_or_b64 exec, exec, s[2:3]
	s_nop 0
